# GDN scan serial wave: K^T fragment reads and decay broadcast of the state update issued in the previous segment (after its MFMAs), so the update starts with operands in registers
# baseline (speedup 1.0000x reference)
.LBB0_521:
	s_mov_b32 s52, 0x8800
	s_waitcnt lgkmcnt(0)
	v_pk_mul_f32 v[50:51], v[2:3], v[194:195] op_sel_hi:[1,0]
	v_pk_mul_f32 v[48:49], v[0:1], v[194:195] op_sel_hi:[1,0]
	v_pk_mul_f32 v[46:47], v[6:7], v[194:195] op_sel_hi:[1,0]
	v_pk_mul_f32 v[44:45], v[4:5], v[194:195] op_sel_hi:[1,0]
	v_pk_mul_f32 v[42:43], v[10:11], v[194:195] op_sel_hi:[1,0]
	v_pk_mul_f32 v[40:41], v[8:9], v[194:195] op_sel_hi:[1,0]
	v_pk_mul_f32 v[38:39], v[14:15], v[194:195] op_sel_hi:[1,0]
	v_pk_mul_f32 v[36:37], v[12:13], v[194:195] op_sel_hi:[1,0]
	v_pk_mul_f32 v[14:15], v[22:23], v[194:195] op_sel_hi:[1,0]
	v_pk_mul_f32 v[12:13], v[20:21], v[194:195] op_sel_hi:[1,0]
	v_pk_mul_f32 v[10:11], v[26:27], v[194:195] op_sel_hi:[1,0]
	v_pk_mul_f32 v[8:9], v[24:25], v[194:195] op_sel_hi:[1,0]
	v_pk_mul_f32 v[6:7], v[30:31], v[194:195] op_sel_hi:[1,0]
	v_pk_mul_f32 v[4:5], v[28:29], v[194:195] op_sel_hi:[1,0]
	v_pk_mul_f32 v[2:3], v[34:35], v[194:195] op_sel_hi:[1,0]
	v_pk_mul_f32 v[0:1], v[32:33], v[194:195] op_sel_hi:[1,0]
	s_nop 0
	s_waitcnt lgkmcnt(0)
	s_waitcnt lgkmcnt(0)
	s_waitcnt lgkmcnt(0)
	s_waitcnt lgkmcnt(0)
	s_nop 0
	v_mfma_f32_16x16x32_bf16 v[18:21], v[176:179], v[88:91], v[48:51]
	v_mfma_f32_16x16x32_bf16 v[22:25], v[180:183], v[88:91], v[44:47]
	v_mfma_f32_16x16x32_bf16 v[26:29], v[184:187], v[88:91], v[40:43]
	v_mfma_f32_16x16x32_bf16 v[30:33], v[188:191], v[88:91], v[36:39]
	v_mfma_f32_16x16x32_bf16 v[34:37], v[52:55], v[88:91], v[12:15]
	v_mfma_f32_16x16x32_bf16 v[38:41], v[56:59], v[88:91], v[8:11]
	v_mfma_f32_16x16x32_bf16 v[42:45], v[128:131], v[88:91], v[4:7]
	v_mfma_f32_16x16x32_bf16 v[46:49], v[132:135], v[88:91], v[0:3]
	v_mfma_f32_16x16x32_bf16 v[0:3], v[136:139], v[84:87], v[18:21]
	v_mfma_f32_16x16x32_bf16 v[4:7], v[140:143], v[84:87], v[22:25]
	v_mfma_f32_16x16x32_bf16 v[8:11], v[144:147], v[84:87], v[26:29]
	v_mfma_f32_16x16x32_bf16 v[12:15], v[148:151], v[84:87], v[30:33]
	v_mfma_f32_16x16x32_bf16 v[20:23], v[152:155], v[84:87], v[34:37]
	v_cvt_pk_bf16_f32 v36, v0, v1
	v_cvt_pk_bf16_f32 v37, v2, v3
	v_mfma_f32_16x16x32_bf16 v[24:27], v[156:159], v[84:87], v[38:41]
	v_cvt_pk_bf16_f32 v38, v4, v5
	v_cvt_pk_bf16_f32 v39, v6, v7
	ds_write_b128 v119, v[36:39]
	v_mfma_f32_16x16x32_bf16 v[28:31], v[160:163], v[84:87], v[42:45]
	v_cvt_pk_bf16_f32 v36, v8, v9
	v_cvt_pk_bf16_f32 v37, v10, v11
	v_cvt_pk_bf16_f32 v38, v12, v13
	v_mfma_f32_16x16x32_bf16 v[32:35], v[164:167], v[84:87], v[46:49]
	v_cvt_pk_bf16_f32 v39, v14, v15
	ds_write_b128 v119, v[36:39] offset:1024
	v_cvt_pk_bf16_f32 v36, v20, v21
	v_cvt_pk_bf16_f32 v37, v22, v23
	v_cvt_pk_bf16_f32 v38, v24, v25
	v_cvt_pk_bf16_f32 v39, v26, v27
	ds_write_b128 v119, v[36:39] offset:2048
	v_cvt_pk_bf16_f32 v36, v28, v29
	v_cvt_pk_bf16_f32 v37, v30, v31
	v_cvt_pk_bf16_f32 v38, v32, v33
	v_cvt_pk_bf16_f32 v39, v34, v35
	ds_write_b128 v119, v[36:39] offset:3072

.LBB0_528:
	v_mov_b64_e32 v[90:91], v[58:59]
	v_mov_b64_e32 v[86:87], v[54:55]
	s_andn2_b64 vcc, exec, s[60:61]
	v_mov_b32_e32 v63, v59
	v_mov_b32_e32 v62, v58
	v_mov_b32_e32 v61, v57
	v_mov_b32_e32 v60, v56
	v_mov_b32_e32 v83, v55
	v_mov_b32_e32 v82, v54
	v_mov_b32_e32 v81, v53
	v_mov_b32_e32 v80, v52
	v_mov_b64_e32 v[88:89], v[56:57]
	v_mov_b64_e32 v[84:85], v[52:53]
	s_cbranch_vccnz .LBB0_530
	v_add_u32_e32 v16, s88, v123
	ds_read_b64 v[64:65], v16 offset:0
	ds_read_b64 v[66:67], v16 offset:32
	ds_read_b64 v[68:69], v16 offset:0x1100
	ds_read_b64 v[70:71], v16 offset:0x1120
	ds_read_b64 v[72:73], v16 offset:0x2200
	ds_read_b64 v[74:75], v16 offset:0x2220
	ds_read_b64 v[76:77], v16 offset:0x3300
	ds_read_b64 v[78:79], v16 offset:0x3320
	ds_read_b64 v[80:81], v16 offset:64
	ds_read_b64 v[82:83], v16 offset:0x60
	ds_read_b64 v[84:85], v16 offset:0x1140
	ds_read_b64 v[86:87], v16 offset:0x1160
	ds_read_b64 v[88:89], v16 offset:0x2240
	ds_read_b64 v[90:91], v16 offset:0x2260
	ds_read_b64 v[128:129], v16 offset:0x3340
	ds_read_b64 v[130:131], v16 offset:0x3360
	ds_read_b64 v[132:133], v16 offset:0x80
	ds_read_b64 v[134:135], v16 offset:0xa0
	ds_read_b64 v[136:137], v16 offset:0x1180
	ds_read_b64 v[138:139], v16 offset:0x11a0
	ds_read_b64 v[140:141], v16 offset:0x2280
	ds_read_b64 v[142:143], v16 offset:0x22a0
	ds_read_b64 v[144:145], v16 offset:0x3380
	ds_read_b64 v[146:147], v16 offset:0x33a0
	ds_read_b64 v[148:149], v16 offset:0xc0
	ds_read_b64 v[150:151], v16 offset:0xe0
	ds_read_b64 v[152:153], v16 offset:0x11c0
	ds_read_b64 v[154:155], v16 offset:0x11e0
	ds_read_b64 v[156:157], v16 offset:0x22c0
	ds_read_b64 v[158:159], v16 offset:0x22e0
	ds_read_b64 v[160:161], v16 offset:0x33c0
	ds_read_b64 v[162:163], v16 offset:0x33e0
	s_nop 0
	s_waitcnt lgkmcnt(0)
	v_cvt_pk_bf16_f32 v60, v0, v1
	v_cvt_pk_bf16_f32 v61, v2, v3
	v_cvt_pk_bf16_f32 v62, v4, v5
	s_waitcnt lgkmcnt(0)
	s_waitcnt lgkmcnt(0)
	v_cvt_pk_bf16_f32 v63, v6, v7
	v_cvt_pk_bf16_f32 v164, v8, v9
	v_cvt_pk_bf16_f32 v165, v10, v11
	v_cvt_pk_bf16_f32 v166, v12, v13
	v_cvt_pk_bf16_f32 v167, v14, v15
	s_waitcnt lgkmcnt(0)
	s_nop 0
	v_mfma_f32_16x16x32_bf16 v[64:67], v[64:67], v[60:63], 0
	v_add3_u32 v16, s88, v124, v127
	v_mfma_f32_16x16x32_bf16 v[68:71], v[68:71], v[60:63], 0
	v_mfma_f32_16x16x32_bf16 v[72:75], v[72:75], v[60:63], 0
	v_mfma_f32_16x16x32_bf16 v[60:63], v[76:79], v[60:63], 0
	v_cvt_pk_bf16_f32 v76, v20, v21
	v_cvt_pk_bf16_f32 v77, v22, v23
	v_cvt_pk_bf16_f32 v78, v24, v25
	v_mfma_f32_16x16x32_bf16 v[64:67], v[80:83], v[164:167], v[64:67]
	v_cvt_pk_bf16_f32 v79, v26, v27
	v_cvt_pk_bf16_f32 v80, v28, v29
	v_cvt_pk_bf16_f32 v81, v30, v31
	v_mfma_f32_16x16x32_bf16 v[68:71], v[84:87], v[164:167], v[68:71]
	v_cvt_pk_bf16_f32 v82, v32, v33
	v_cvt_pk_bf16_f32 v83, v34, v35
	v_mfma_f32_16x16x32_bf16 v[72:75], v[88:91], v[164:167], v[72:75]
	v_mfma_f32_16x16x32_bf16 v[60:63], v[128:131], v[164:167], v[60:63]
	v_mfma_f32_16x16x32_bf16 v[64:67], v[132:135], v[76:79], v[64:67]
	v_mfma_f32_16x16x32_bf16 v[68:71], v[136:139], v[76:79], v[68:71]
	v_mfma_f32_16x16x32_bf16 v[72:75], v[140:143], v[76:79], v[72:75]
	v_mfma_f32_16x16x32_bf16 v[60:63], v[144:147], v[76:79], v[60:63]
	v_mfma_f32_16x16x32_bf16 v[64:67], v[148:151], v[80:83], v[64:67]
	v_mfma_f32_16x16x32_bf16 v[68:71], v[152:155], v[80:83], v[68:71]
	v_mfma_f32_16x16x32_bf16 v[72:75], v[156:159], v[80:83], v[72:75]
	v_mfma_f32_16x16x32_bf16 v[60:63], v[160:163], v[80:83], v[60:63]
	v_lshlrev_b32_e32 v192, 2, v234
	v_and_b32_e32 v192, 0x100, v192
	v_add_u32_e32 v192, s35, v192
	ds_bpermute_b32 v194, v192, v120
	v_add_u32_e32 v192, s88, v121
	v_add_u32_e32 v192, v192, v126
	v_add_u32_e32 v192, 0x8800, v192
	ds_read_b64 v[176:177], v192 offset:0
	ds_read_b64 v[178:179], v192 offset:32
	ds_read_b64 v[180:181], v192 offset:0x900
	ds_read_b64 v[182:183], v192 offset:0x920
	ds_read_b64 v[184:185], v192 offset:0x1200
	ds_read_b64 v[186:187], v192 offset:0x1220
	ds_read_b64 v[188:189], v192 offset:0x1b00
	ds_read_b64 v[190:191], v192 offset:0x1b20
	ds_read_b64 v[52:53], v192 offset:0x2400
	ds_read_b64 v[54:55], v192 offset:0x2420
	ds_read_b64 v[56:57], v192 offset:0x2d00
	ds_read_b64 v[58:59], v192 offset:0x2d20
	ds_read_b64 v[128:129], v192 offset:0x3600
	ds_read_b64 v[130:131], v192 offset:0x3620
	ds_read_b64 v[132:133], v192 offset:0x3f00
	ds_read_b64 v[134:135], v192 offset:0x3f20
	ds_read_b64 v[136:137], v192 offset:64
	ds_read_b64 v[138:139], v192 offset:0x60
	ds_read_b64 v[140:141], v192 offset:0x940
	ds_read_b64 v[142:143], v192 offset:0x960
	ds_read_b64 v[144:145], v192 offset:0x1240
	ds_read_b64 v[146:147], v192 offset:0x1260
	ds_read_b64 v[148:149], v192 offset:0x1b40
	ds_read_b64 v[150:151], v192 offset:0x1b60
	ds_read_b64 v[152:153], v192 offset:0x2440
	ds_read_b64 v[154:155], v192 offset:0x2460
	ds_read_b64 v[156:157], v192 offset:0x2d40
	ds_read_b64 v[158:159], v192 offset:0x2d60
	ds_read_b64 v[160:161], v192 offset:0x3640
	ds_read_b64 v[162:163], v192 offset:0x3660
	ds_read_b64 v[164:165], v192 offset:0x3f40
	ds_read_b64 v[166:167], v192 offset:0x3f60
	ds_read_u16 v18, v16 offset:62464
	ds_read_u16 v19, v16 offset:62496
	ds_read_u16 v76, v16 offset:62528
	ds_read_u16 v77, v16 offset:62560
	ds_read_u16 v78, v16 offset:62976
	ds_read_u16 v79, v16 offset:63008
	ds_read_u16 v80, v16 offset:63040
	ds_read_u16 v81, v16 offset:63072
	s_waitcnt lgkmcnt(7)
	v_lshlrev_b32_e32 v18, 16, v18
	s_waitcnt lgkmcnt(6)
	v_lshlrev_b32_e32 v19, 16, v19
	v_sub_f32_e32 v18, v18, v64
	v_sub_f32_e32 v19, v19, v65
	s_waitcnt lgkmcnt(5)
	v_lshlrev_b32_e32 v64, 16, v76
	s_waitcnt lgkmcnt(4)
	v_lshlrev_b32_e32 v65, 16, v77
	v_sub_f32_e32 v64, v64, v66
	v_sub_f32_e32 v65, v65, v67
	s_waitcnt lgkmcnt(3)
	v_lshlrev_b32_e32 v66, 16, v78
	s_waitcnt lgkmcnt(2)
	v_lshlrev_b32_e32 v67, 16, v79
	v_sub_f32_e32 v66, v66, v68
	v_sub_f32_e32 v67, v67, v69
	s_waitcnt lgkmcnt(1)
	v_lshlrev_b32_e32 v68, 16, v80
	s_waitcnt lgkmcnt(0)
	v_lshlrev_b32_e32 v69, 16, v81
	v_sub_f32_e32 v68, v68, v70
	v_sub_f32_e32 v69, v69, v71
	ds_read_u16 v70, v16 offset:63488
	ds_read_u16 v71, v16 offset:63520
	ds_read_u16 v76, v16 offset:63552
	ds_read_u16 v77, v16 offset:63584
	ds_read_u16 v78, v16 offset:64000
	ds_read_u16 v79, v16 offset:64032
	ds_read_u16 v80, v16 offset:64064
	ds_read_u16 v16, v16 offset:64096
	s_waitcnt lgkmcnt(7)
	v_lshlrev_b32_e32 v70, 16, v70
	v_sub_f32_e32 v70, v70, v72
	s_waitcnt lgkmcnt(5)
	v_lshlrev_b32_e32 v72, 16, v76
	v_lshlrev_b32_e32 v71, 16, v71
	v_sub_f32_e32 v72, v72, v74
	s_waitcnt lgkmcnt(3)
	v_lshlrev_b32_e32 v74, 16, v78
	v_sub_f32_e32 v71, v71, v73
	v_lshlrev_b32_e32 v73, 16, v77
	v_sub_f32_e32 v74, v74, v60
	s_waitcnt lgkmcnt(2)
	v_lshlrev_b32_e32 v60, 16, v79
	v_sub_f32_e32 v73, v73, v75
	v_sub_f32_e32 v75, v60, v61
	s_waitcnt lgkmcnt(1)
	v_lshlrev_b32_e32 v60, 16, v80
	v_sub_f32_e32 v76, v60, v62
	s_waitcnt lgkmcnt(0)
	v_lshlrev_b32_e32 v16, 16, v16
	v_sub_f32_e32 v16, v16, v63
	v_cvt_pk_bf16_f32 v60, v18, v19
	v_cvt_pk_bf16_f32 v61, v64, v65
	v_cvt_pk_bf16_f32 v62, v66, v67
	v_cvt_pk_bf16_f32 v63, v68, v69
	v_cvt_pk_bf16_f32 v80, v70, v71
	v_cvt_pk_bf16_f32 v81, v72, v73
	v_cvt_pk_bf16_f32 v82, v74, v75
	v_cvt_pk_bf16_f32 v83, v76, v16
	v_mov_b64_e32 v[78:79], v[50:51]
	v_mov_b64_e32 v[74:75], v[46:47]
	v_mov_b64_e32 v[66:67], v[42:43]
	v_mov_b64_e32 v[70:71], v[38:39]
	v_mov_b64_e32 v[90:91], v[62:63]
	v_mov_b64_e32 v[86:87], v[82:83]
	v_add_u32_e32 v18, 0x20800, v118
	v_mov_b64_e32 v[76:77], v[48:49]
	v_mov_b64_e32 v[72:73], v[44:45]
	v_mov_b64_e32 v[64:65], v[40:41]
	v_mov_b64_e32 v[68:69], v[36:37]
	v_mov_b64_e32 v[88:89], v[60:61]
	v_mov_b64_e32 v[84:85], v[80:81]
	ds_write_b128 v18, v[60:63]
	ds_write_b128 v18, v[80:83] offset:1024
